# GEMM K-loop regrouped: 4 phases of 32 MFMA per 2 k-tiles instead of 8x16 (same instructions, LDS-DMA schedule re-derived, waits vmcnt(8)+lgkmcnt(0) before barrier)
# speedup vs baseline: 1.0212x; 1.0102x over previous
; #define PG8_STAGE(bufoff, gbase, voff) do { _Pragma("unroll") for (int _i = 0; _i < 2; ++_i) \
;         __builtin_amdgcn_global_load_lds((const unsigned*)((const char*)(gbase) + (voff)[_i]), (LAS unsigned*)(lds + (bufoff) + ldsw + _i * 8192), 16, 0, 0); } while (0)
; #define PG8_WAIT_V(n) asm volatile("s_waitcnt vmcnt(" #n ")" ::: "memory")
; #define PG8_BAR __builtin_amdgcn_s_barrier()
; template <class Epi>
; __device__ __forceinline__ void gemm_phase(LAS unsigned char* lds, const Gemm g, const StaticOrder& S, const Epi& E, const bool perm) {
;     ...
;     PG8_STAGE(PG8_SB(0, 0), cB, voffB); PG8_STAGE(PG8_SA(0, 0), cA, voffA); PG8_STAGE(PG8_SB(0, 1), cB + hstep, voffB); PG8_STAGE(PG8_SA(0, 1), cA + hstep, voffA);
;     if (wr == 1) PG8_BAR;
;     PG8_WAIT_V(4); PG8_BAR;
;     PG8_STAGE(PG8_SB(1, 0), cB + kstep, voffB); PG8_STAGE(PG8_SA(1, 0), cA + kstep, voffA); PG8_STAGE(PG8_SB(1, 1), cB + hstep + kstep, voffB);
;     PG8_WAIT_V(6); PG8_BAR;
.LBB0_453:
	v_mov_b32_e32 v213, v185
	v_lshl_add_u64 v[8:9], s[22:23], 0, v[212:213]
	v_mov_b32_e32 v209, v185
	v_lshl_add_u64 v[10:11], s[22:23], 0, v[208:209]
	v_mov_b32_e32 v211, v185
	s_add_i32 m0, s36, 0x18000
	v_lshl_add_u64 v[8:9], v[8:9], 0, s[74:75]
	v_lshl_add_u64 v[12:13], s[6:7], 0, v[210:211]
	v_mov_b32_e32 v207, v185
	s_waitcnt vmcnt(2)
	s_barrier
	global_load_lds_dwordx4 v[8:9], off
	v_lshl_add_u64 v[8:9], v[10:11], 0, s[74:75]
	s_add_i32 m0, s36, 0x1a000
	s_add_i32 s14, s36, 0x8000
	s_waitcnt lgkmcnt(0)
	v_lshl_add_u64 v[14:15], s[6:7], 0, v[206:207]
	global_load_lds_dwordx4 v[8:9], off
	v_lshl_add_u64 v[8:9], v[12:13], 0, s[74:75]
	s_mov_b32 m0, s14
	s_add_i32 s15, s36, 0xa000
	v_lshl_add_u64 v[16:17], s[0:1], 0, v[212:213]
	global_load_lds_dwordx4 v[8:9], off
	v_lshl_add_u64 v[8:9], v[14:15], 0, s[74:75]
	s_mov_b32 m0, s15
	v_lshl_add_u64 v[18:19], s[0:1], 0, v[208:209]
	global_load_lds_dwordx4 v[8:9], off
	s_add_i32 m0, s36, 0x1c000
	v_lshl_add_u64 v[8:9], v[16:17], 0, s[74:75]
	global_load_lds_dwordx4 v[8:9], off
	v_lshl_add_u64 v[8:9], v[18:19], 0, s[74:75]
	s_add_i32 m0, s36, 0x1e000
	v_bfe_u32 v7, v0, 4, 2
	global_load_lds_dwordx4 v[8:9], off
	v_and_b32_e32 v187, 15, v0
	v_lshlrev_b32_e32 v8, 4, v7
	v_lshlrev_b32_e32 v0, 2, v0
	s_and_b32 s64, s9, 3
	v_lshl_or_b32 v8, v187, 6, v8
	s_lshl_b32 s0, s8, 13
	v_and_b32_e32 v0, 32, v0
	v_bitop3_b32 v9, v8, s0, v0 bitop3:0xde
	s_lshl_b32 s0, s64, 12
	s_lshl_b32 s39, s10, 3
	v_bitop3_b32 v245, v8, s0, v0 bitop3:0xde
	v_cvt_f32_u32_e32 v0, s39
	s_lshl_b32 s0, s10, 4
	v_writelane_b32 v255, s0, 62
	s_sub_i32 s0, 0, s39
	v_rcp_iflag_f32_e32 v0, v0
	s_waitcnt vmcnt(6)
	s_lshr_b32 s65, s24, 6
	s_cmp_eq_u32 s5, 7
	s_cselect_b32 s65, 2, s65
	s_lshl_b32 s76, s8, 6
	v_mul_f32_e32 v0, 0x4f7ffffe, v0
	v_cvt_u32_f32_e32 v0, v0
	s_lshl_b32 s77, s64, 5
	v_or_b32_e32 v244, s76, v187
	s_add_i32 s27, s65, -2
	v_readfirstlane_b32 s1, v0
	s_mul_i32 s0, s0, s1
	v_add_u32_e32 v0, v5, v2
	s_mul_hi_u32 s0, s1, s0
	v_add_lshl_u32 v184, v0, v4, 1
	v_add_u32_e32 v0, v6, v1
	s_add_i32 s0, s1, s0
	v_lshl_add_u64 v[214:215], s[80:81], 0, v[184:185]
	v_add_lshl_u32 v184, v0, v3, 1
	v_lshl_or_b32 v246, v7, 3, s77
	s_mov_b32 s24, 0
	v_cmp_eq_u32_e64 s[8:9], 0, v7
	v_lshlrev_b32_e32 v247, 2, v7
	s_ashr_i32 s92, s30, 31
	s_mov_b32 s63, s25
	s_mov_b32 s59, s58
	s_mov_b32 s16, s58
	s_mov_b32 s17, s58
	v_writelane_b32 v255, s0, 63
	v_lshl_add_u64 v[216:217], s[80:81], 0, v[184:185]
	v_add_u32_e32 v248, 0, v9
	s_barrier
	s_branch .LBB0_455

; #define PG8_STAGE(bufoff, gbase, voff) do { _Pragma("unroll") for (int _i = 0; _i < 2; ++_i) \
;         __builtin_amdgcn_global_load_lds((const unsigned*)((const char*)(gbase) + (voff)[_i]), (LAS unsigned*)(lds + (bufoff) + ldsw + _i * 8192), 16, 0, 0); } while (0)
; #define PG8_LDA(dst, b, h) do { _Pragma("unroll") for (int m = 0; m < 4; ++m) _Pragma("unroll") for (int k = 0; k < 2; ++k) dst[m][k] = *(const LAS bf16x8*)(lds + PG8_SA(b, h) + aoff + m * 2048 + k * 1024); } while (0)
; #define PG8_LDB(dst, b, h) do { _Pragma("unroll") for (int n = 0; n < 2; ++n) _Pragma("unroll") for (int k = 0; k < 2; ++k) dst[n][k] = *(const LAS bf16x8*)(lds + PG8_SB(b, h) + boff + n * 2048 + k * 1024); } while (0)
; #define PG8_MMA(ai, bj, At, Bt) do { __builtin_amdgcn_s_setprio(1); _Pragma("unroll") for (int m = 0; m < 4; ++m) _Pragma("unroll") for (int n = 0; n < 2; ++n) _Pragma("unroll") for (int k = 0; k < 2; ++k) \
;         acc[ai][bj][m][n] = __builtin_amdgcn_mfma_f32_16x16x32_bf16(Bt[n][k], At[m][k], acc[ai][bj][m][n], 0, 0, 0); __builtin_amdgcn_s_setprio(0); } while (0)
; #define PG8_WAIT_V(n) asm volatile("s_waitcnt vmcnt(" #n ")" ::: "memory")
; #define PG8_WAIT_L(n) asm volatile("s_waitcnt lgkmcnt(" #n ")" ::: "memory")
; #define PG8_BAR __builtin_amdgcn_s_barrier()
; #define PG8_SCHED __builtin_amdgcn_sched_barrier(0)
; template <class Epi>
; __device__ __forceinline__ void gemm_phase(LAS unsigned char* lds, const Gemm g, const StaticOrder& S, const Epi& E, const bool perm) {
;     ...
;             PG8_LDB(B0, 0, 0); PG8_SCHED; PG8_LDA(At, 0, 0); PG8_STAGE(PG8_SA(1, 1), a1 + hstep, voffA);
;             PG8_WAIT_L(8); PG8_BAR; PG8_WAIT_L(0); PG8_MMA(0, 0, At, B0); PG8_BAR; PG8_SCHED;
;             PG8_LDB(B1, 0, 1); PG8_STAGE(PG8_SB(0, 0), b2, voffB);
;             PG8_BAR; PG8_WAIT_L(0); PG8_MMA(0, 1, At, B1); PG8_BAR;
;             PG8_LDA(At, 0, 1); PG8_STAGE(PG8_SA(0, 0), a2, voffA);
;             PG8_BAR; PG8_WAIT_L(0); PG8_MMA(1, 0, At, B0); PG8_BAR; PG8_SCHED;
;             PG8_STAGE(PG8_SB(0, 1), b2 + hstep, voffB);
;             PG8_WAIT_V(6); PG8_BAR; PG8_MMA(1, 1, At, B1); PG8_BAR;
.LBB0_462:
	s_add_i32 s61, s60, 2
	s_add_u32 s22, s6, 0x80
	s_addc_u32 s23, s7, 0
	s_add_i32 s40, 0, 0x10000
	v_add_u32_e32 v140, s40, v245
	s_waitcnt lgkmcnt(0)
	ds_read_b128 v[128:131], v140
	ds_read_b128 v[132:135], v140 offset:1024
	ds_read_b128 v[136:139], v140 offset:2048
	ds_read_b128 v[140:143], v140 offset:3072
	s_cmp_eq_u32 s27, s60
	s_cselect_b32 s23, s1, s23
	s_cselect_b32 s22, s0, s22
	s_cselect_b32 s47, s13, s78
	s_cselect_b32 s46, s12, s55
	v_lshl_add_u64 v[176:177], s[6:7], 0, v[214:215]
	s_add_i32 m0, s36, 0xc000
	ds_read_b128 v[144:147], v248
	ds_read_b128 v[148:151], v248 offset:1024
	ds_read_b128 v[152:155], v248 offset:2048
	ds_read_b128 v[156:159], v248 offset:3072
	ds_read_b128 v[160:163], v248 offset:4096
	ds_read_b128 v[164:167], v248 offset:5120
	ds_read_b128 v[168:171], v248 offset:6144
	ds_read_b128 v[172:175], v248 offset:7168
	global_load_lds_dwordx4 v[176:177], off
	v_lshl_add_u64 v[176:177], s[6:7], 0, v[216:217]
	s_add_i32 m0, s36, 0xe000
	s_nop 0
	global_load_lds_dwordx4 v[176:177], off
	s_add_i32 s60, 0, 0x14000
	s_add_i32 s40, s40, s31
	v_add_u32_e32 v184, s60, v245
	ds_read_b128 v[176:179], v184
	ds_read_b128 v[180:183], v184 offset:1024
	ds_read_b128 v[222:225], v184 offset:2048
	ds_read_b128 v[226:229], v184 offset:3072
	s_waitcnt vmcnt(8)
	s_waitcnt lgkmcnt(0)
	s_barrier
	s_setprio 1
	v_mfma_f32_16x16x32_bf16 v[124:127], v[128:131], v[144:147], v[124:127]
	v_mfma_f32_16x16x32_bf16 v[120:123], v[136:139], v[144:147], v[120:123]
	v_mfma_f32_16x16x32_bf16 v[108:111], v[128:131], v[152:155], v[108:111]
	v_mfma_f32_16x16x32_bf16 v[104:107], v[136:139], v[152:155], v[104:107]
	v_mfma_f32_16x16x32_bf16 v[92:95], v[128:131], v[160:163], v[92:95]
	v_mfma_f32_16x16x32_bf16 v[88:91], v[136:139], v[160:163], v[88:91]
	v_mfma_f32_16x16x32_bf16 v[76:79], v[128:131], v[168:171], v[76:79]
	v_mfma_f32_16x16x32_bf16 v[72:75], v[136:139], v[168:171], v[72:75]
	v_mfma_f32_16x16x32_bf16 v[124:127], v[132:135], v[148:151], v[124:127]
	v_mfma_f32_16x16x32_bf16 v[120:123], v[140:143], v[148:151], v[120:123]
	v_mfma_f32_16x16x32_bf16 v[108:111], v[132:135], v[156:159], v[108:111]
	v_mfma_f32_16x16x32_bf16 v[104:107], v[140:143], v[156:159], v[104:107]
	v_mfma_f32_16x16x32_bf16 v[92:95], v[132:135], v[164:167], v[92:95]
	v_mfma_f32_16x16x32_bf16 v[88:91], v[140:143], v[164:167], v[88:91]
	v_mfma_f32_16x16x32_bf16 v[76:79], v[132:135], v[172:175], v[76:79]
	v_mfma_f32_16x16x32_bf16 v[72:75], v[140:143], v[172:175], v[72:75]
	v_mfma_f32_16x16x32_bf16 v[116:119], v[176:179], v[144:147], v[116:119]
	v_mfma_f32_16x16x32_bf16 v[112:115], v[222:225], v[144:147], v[112:115]
	v_mfma_f32_16x16x32_bf16 v[100:103], v[176:179], v[152:155], v[100:103]
	v_mfma_f32_16x16x32_bf16 v[96:99], v[222:225], v[152:155], v[96:99]
	v_mfma_f32_16x16x32_bf16 v[84:87], v[176:179], v[160:163], v[84:87]
	v_mfma_f32_16x16x32_bf16 v[80:83], v[222:225], v[160:163], v[80:83]
	v_mfma_f32_16x16x32_bf16 v[68:71], v[176:179], v[168:171], v[68:71]
	v_mfma_f32_16x16x32_bf16 v[64:67], v[222:225], v[168:171], v[64:67]
	v_mfma_f32_16x16x32_bf16 v[116:119], v[180:183], v[148:151], v[116:119]
	v_mfma_f32_16x16x32_bf16 v[112:115], v[226:229], v[148:151], v[112:115]
	v_mfma_f32_16x16x32_bf16 v[100:103], v[180:183], v[156:159], v[100:103]
	v_mfma_f32_16x16x32_bf16 v[96:99], v[226:229], v[156:159], v[96:99]
	v_mfma_f32_16x16x32_bf16 v[84:87], v[180:183], v[164:167], v[84:87]
	v_mfma_f32_16x16x32_bf16 v[80:83], v[226:229], v[164:167], v[80:83]
	v_mfma_f32_16x16x32_bf16 v[68:71], v[180:183], v[172:175], v[68:71]
	v_mfma_f32_16x16x32_bf16 v[64:67], v[226:229], v[172:175], v[64:67]
	s_setprio 0
	s_barrier
	ds_read_b128 v[144:147], v248 offset:16384
	ds_read_b128 v[148:151], v248 offset:17408
	ds_read_b128 v[152:155], v248 offset:18432
	ds_read_b128 v[156:159], v248 offset:19456
	ds_read_b128 v[160:163], v248 offset:20480
	ds_read_b128 v[164:167], v248 offset:21504
	ds_read_b128 v[168:171], v248 offset:22528
	ds_read_b128 v[172:175], v248 offset:23552
	v_lshl_add_u64 v[230:231], s[46:47], 0, v[212:213]
	s_mov_b32 m0, s40
	s_nop 0
	global_load_lds_dwordx4 v[230:231], off
	v_lshl_add_u64 v[232:233], s[46:47], 0, v[208:209]
	s_add_i32 m0, s40, 0x2000
	s_nop 0
	global_load_lds_dwordx4 v[232:233], off
	v_lshl_add_u64 v[250:251], s[22:23], 0, v[210:211]
	s_mov_b32 m0, s36
	s_nop 0
	global_load_lds_dwordx4 v[250:251], off
	v_lshl_add_u64 v[252:253], s[22:23], 0, v[206:207]
	s_mov_b32 m0, s37
	s_nop 0
	global_load_lds_dwordx4 v[252:253], off
	s_add_u32 s40, s46, s80
	s_addc_u32 s41, s47, s81
	s_add_i32 s46, s60, s31
	v_lshl_add_u64 v[238:239], s[40:41], 0, v[212:213]
	s_mov_b32 m0, s46
	v_lshl_add_u64 v[240:241], s[40:41], 0, v[208:209]
	global_load_lds_dwordx4 v[238:239], off
	s_add_i32 m0, s46, 0x2000
	s_nop 0
	global_load_lds_dwordx4 v[240:241], off
	s_waitcnt vmcnt(8)
	s_waitcnt lgkmcnt(0)
	s_barrier
; #define PG8_STAGE(bufoff, gbase, voff) do { _Pragma("unroll") for (int _i = 0; _i < 2; ++_i) \
;         __builtin_amdgcn_global_load_lds((const unsigned*)((const char*)(gbase) + (voff)[_i]), (LAS unsigned*)(lds + (bufoff) + ldsw + _i * 8192), 16, 0, 0); } while (0)
; #define PG8_LDA(dst, b, h) do { _Pragma("unroll") for (int m = 0; m < 4; ++m) _Pragma("unroll") for (int k = 0; k < 2; ++k) dst[m][k] = *(const LAS bf16x8*)(lds + PG8_SA(b, h) + aoff + m * 2048 + k * 1024); } while (0)
; #define PG8_LDB(dst, b, h) do { _Pragma("unroll") for (int n = 0; n < 2; ++n) _Pragma("unroll") for (int k = 0; k < 2; ++k) dst[n][k] = *(const LAS bf16x8*)(lds + PG8_SB(b, h) + boff + n * 2048 + k * 1024); } while (0)
; #define PG8_MMA(ai, bj, At, Bt) do { __builtin_amdgcn_s_setprio(1); _Pragma("unroll") for (int m = 0; m < 4; ++m) _Pragma("unroll") for (int n = 0; n < 2; ++n) _Pragma("unroll") for (int k = 0; k < 2; ++k) \
;         acc[ai][bj][m][n] = __builtin_amdgcn_mfma_f32_16x16x32_bf16(Bt[n][k], At[m][k], acc[ai][bj][m][n], 0, 0, 0); __builtin_amdgcn_s_setprio(0); } while (0)
; #define PG8_WAIT_V(n) asm volatile("s_waitcnt vmcnt(" #n ")" ::: "memory")
; #define PG8_WAIT_L(n) asm volatile("s_waitcnt lgkmcnt(" #n ")" ::: "memory")
; #define PG8_BAR __builtin_amdgcn_s_barrier()
; #define PG8_SCHED __builtin_amdgcn_sched_barrier(0)
; template <class Epi>
; __device__ __forceinline__ void gemm_phase(LAS unsigned char* lds, const Gemm g, const StaticOrder& S, const Epi& E, const bool perm) {
;     ...
;             PG8_BAR; PG8_WAIT_L(0); PG8_MMA(1, 0, At, B0); PG8_BAR; PG8_SCHED;
;             PG8_STAGE(PG8_SB(0, 1), b2 + hstep, voffB);
;             PG8_WAIT_V(6); PG8_BAR; PG8_MMA(1, 1, At, B1); PG8_BAR;
;             PG8_LDB(B0, 1, 0); PG8_SCHED; PG8_LDA(At, 1, 0); PG8_STAGE(PG8_SA(0, 1), a2 + hstep, voffA);
;             PG8_WAIT_L(8); PG8_BAR; PG8_WAIT_L(0); PG8_MMA(0, 0, At, B0); PG8_BAR; PG8_SCHED;
;             PG8_LDB(B1, 1, 1); PG8_STAGE(PG8_SB(1, 0), b3, voffB);
;             PG8_BAR; PG8_WAIT_L(0); PG8_MMA(0, 1, At, B1); PG8_BAR;
;             PG8_LDA(At, 1, 1); PG8_STAGE(PG8_SA(1, 0), a3, voffA);
;             PG8_BAR; PG8_WAIT_L(0); PG8_MMA(1, 0, At, B0); PG8_BAR; PG8_SCHED;
	s_setprio 1
	v_mfma_f32_16x16x32_bf16 v[60:63], v[128:131], v[144:147], v[60:63]
	v_mfma_f32_16x16x32_bf16 v[56:59], v[136:139], v[144:147], v[56:59]
	v_mfma_f32_16x16x32_bf16 v[44:47], v[128:131], v[152:155], v[44:47]
	v_mfma_f32_16x16x32_bf16 v[40:43], v[136:139], v[152:155], v[40:43]
	v_mfma_f32_16x16x32_bf16 v[28:31], v[128:131], v[160:163], v[28:31]
	v_mfma_f32_16x16x32_bf16 v[24:27], v[136:139], v[160:163], v[24:27]
	v_mfma_f32_16x16x32_bf16 v[12:15], v[128:131], v[168:171], v[12:15]
	v_mfma_f32_16x16x32_bf16 v[8:11], v[136:139], v[168:171], v[8:11]
	v_mfma_f32_16x16x32_bf16 v[60:63], v[132:135], v[148:151], v[60:63]
	v_mfma_f32_16x16x32_bf16 v[56:59], v[140:143], v[148:151], v[56:59]
	v_mfma_f32_16x16x32_bf16 v[44:47], v[132:135], v[156:159], v[44:47]
	v_mfma_f32_16x16x32_bf16 v[40:43], v[140:143], v[156:159], v[40:43]
	v_mfma_f32_16x16x32_bf16 v[28:31], v[132:135], v[164:167], v[28:31]
	v_mfma_f32_16x16x32_bf16 v[24:27], v[140:143], v[164:167], v[24:27]
	v_mfma_f32_16x16x32_bf16 v[12:15], v[132:135], v[172:175], v[12:15]
	v_mfma_f32_16x16x32_bf16 v[8:11], v[140:143], v[172:175], v[8:11]
	v_mfma_f32_16x16x32_bf16 v[52:55], v[176:179], v[144:147], v[52:55]
	v_mfma_f32_16x16x32_bf16 v[48:51], v[222:225], v[144:147], v[48:51]
	v_mfma_f32_16x16x32_bf16 v[36:39], v[176:179], v[152:155], v[36:39]
	v_mfma_f32_16x16x32_bf16 v[32:35], v[222:225], v[152:155], v[32:35]
	v_mfma_f32_16x16x32_bf16 v[20:23], v[176:179], v[160:163], v[20:23]
	v_mfma_f32_16x16x32_bf16 v[16:19], v[222:225], v[160:163], v[16:19]
	v_mfma_f32_16x16x32_bf16 v[4:7], v[176:179], v[168:171], v[4:7]
	v_mfma_f32_16x16x32_bf16 v[0:3], v[222:225], v[168:171], v[0:3]
	v_mfma_f32_16x16x32_bf16 v[52:55], v[180:183], v[148:151], v[52:55]
	v_mfma_f32_16x16x32_bf16 v[48:51], v[226:229], v[148:151], v[48:51]
	v_mfma_f32_16x16x32_bf16 v[36:39], v[180:183], v[156:159], v[36:39]
	v_mfma_f32_16x16x32_bf16 v[32:35], v[226:229], v[156:159], v[32:35]
	v_mfma_f32_16x16x32_bf16 v[20:23], v[180:183], v[164:167], v[20:23]
	v_mfma_f32_16x16x32_bf16 v[16:19], v[226:229], v[164:167], v[16:19]
	v_mfma_f32_16x16x32_bf16 v[4:7], v[180:183], v[172:175], v[4:7]
	v_mfma_f32_16x16x32_bf16 v[0:3], v[226:229], v[172:175], v[0:3]
	s_setprio 0
	s_add_i32 s40, 0, 0x18000
	v_add_u32_e32 v140, s40, v245
	s_barrier
	ds_read_b128 v[128:131], v140
	ds_read_b128 v[132:135], v140 offset:1024
	ds_read_b128 v[136:139], v140 offset:2048
	ds_read_b128 v[140:143], v140 offset:3072
	s_add_u32 s22, s22, s80
	s_addc_u32 s23, s23, s81
	s_mov_b32 m0, s34
	v_lshl_add_u64 v[176:177], s[22:23], 0, v[210:211]
	ds_read_b128 v[144:147], v248 offset:32768
	ds_read_b128 v[148:151], v248 offset:33792
	ds_read_b128 v[152:155], v248 offset:34816
	ds_read_b128 v[156:159], v248 offset:35840
	ds_read_b128 v[160:163], v248 offset:36864
	ds_read_b128 v[164:167], v248 offset:37888
	ds_read_b128 v[168:171], v248 offset:38912
	ds_read_b128 v[172:175], v248 offset:39936
	global_load_lds_dwordx4 v[176:177], off
	v_lshl_add_u64 v[176:177], s[22:23], 0, v[206:207]
	s_mov_b32 m0, s35
	s_nop 0
	global_load_lds_dwordx4 v[176:177], off
	s_add_i32 s22, 0, 0x1c000
	s_add_i32 s23, s40, s31
	v_add_u32_e32 v184, s22, v245
	ds_read_b128 v[176:179], v184
	ds_read_b128 v[180:183], v184 offset:1024
	ds_read_b128 v[222:225], v184 offset:2048
	ds_read_b128 v[226:229], v184 offset:3072
	s_waitcnt vmcnt(8)
	s_waitcnt lgkmcnt(0)
	s_barrier
	s_setprio 1
	v_mfma_f32_16x16x32_bf16 v[124:127], v[128:131], v[144:147], v[124:127]
	v_mfma_f32_16x16x32_bf16 v[120:123], v[136:139], v[144:147], v[120:123]
	v_mfma_f32_16x16x32_bf16 v[108:111], v[128:131], v[152:155], v[108:111]
	v_mfma_f32_16x16x32_bf16 v[104:107], v[136:139], v[152:155], v[104:107]
	v_mfma_f32_16x16x32_bf16 v[92:95], v[128:131], v[160:163], v[92:95]
	v_mfma_f32_16x16x32_bf16 v[88:91], v[136:139], v[160:163], v[88:91]
	v_mfma_f32_16x16x32_bf16 v[76:79], v[128:131], v[168:171], v[76:79]
	v_mfma_f32_16x16x32_bf16 v[72:75], v[136:139], v[168:171], v[72:75]
	v_mfma_f32_16x16x32_bf16 v[124:127], v[132:135], v[148:151], v[124:127]
	v_mfma_f32_16x16x32_bf16 v[120:123], v[140:143], v[148:151], v[120:123]
	v_mfma_f32_16x16x32_bf16 v[108:111], v[132:135], v[156:159], v[108:111]
	v_mfma_f32_16x16x32_bf16 v[104:107], v[140:143], v[156:159], v[104:107]
	v_mfma_f32_16x16x32_bf16 v[92:95], v[132:135], v[164:167], v[92:95]
	v_mfma_f32_16x16x32_bf16 v[88:91], v[140:143], v[164:167], v[88:91]
	v_mfma_f32_16x16x32_bf16 v[76:79], v[132:135], v[172:175], v[76:79]
	v_mfma_f32_16x16x32_bf16 v[72:75], v[140:143], v[172:175], v[72:75]
	v_mfma_f32_16x16x32_bf16 v[116:119], v[176:179], v[144:147], v[116:119]
	v_mfma_f32_16x16x32_bf16 v[112:115], v[222:225], v[144:147], v[112:115]
	v_mfma_f32_16x16x32_bf16 v[100:103], v[176:179], v[152:155], v[100:103]
	v_mfma_f32_16x16x32_bf16 v[96:99], v[222:225], v[152:155], v[96:99]
	v_mfma_f32_16x16x32_bf16 v[84:87], v[176:179], v[160:163], v[84:87]
	v_mfma_f32_16x16x32_bf16 v[80:83], v[222:225], v[160:163], v[80:83]
	v_mfma_f32_16x16x32_bf16 v[68:71], v[176:179], v[168:171], v[68:71]
	v_mfma_f32_16x16x32_bf16 v[64:67], v[222:225], v[168:171], v[64:67]
	v_mfma_f32_16x16x32_bf16 v[116:119], v[180:183], v[148:151], v[116:119]
	v_mfma_f32_16x16x32_bf16 v[112:115], v[226:229], v[148:151], v[112:115]
	v_mfma_f32_16x16x32_bf16 v[100:103], v[180:183], v[156:159], v[100:103]
	v_mfma_f32_16x16x32_bf16 v[96:99], v[226:229], v[156:159], v[96:99]
	v_mfma_f32_16x16x32_bf16 v[84:87], v[180:183], v[164:167], v[84:87]
	v_mfma_f32_16x16x32_bf16 v[80:83], v[226:229], v[164:167], v[80:83]
	v_mfma_f32_16x16x32_bf16 v[68:71], v[180:183], v[172:175], v[68:71]
	v_mfma_f32_16x16x32_bf16 v[64:67], v[226:229], v[172:175], v[64:67]
	s_setprio 0
	s_barrier
; #define PG8_STAGE(bufoff, gbase, voff) do { _Pragma("unroll") for (int _i = 0; _i < 2; ++_i) \
;         __builtin_amdgcn_global_load_lds((const unsigned*)((const char*)(gbase) + (voff)[_i]), (LAS unsigned*)(lds + (bufoff) + ldsw + _i * 8192), 16, 0, 0); } while (0)
; #define PG8_LDA(dst, b, h) do { _Pragma("unroll") for (int m = 0; m < 4; ++m) _Pragma("unroll") for (int k = 0; k < 2; ++k) dst[m][k] = *(const LAS bf16x8*)(lds + PG8_SA(b, h) + aoff + m * 2048 + k * 1024); } while (0)
; #define PG8_MMA(ai, bj, At, Bt) do { __builtin_amdgcn_s_setprio(1); _Pragma("unroll") for (int m = 0; m < 4; ++m) _Pragma("unroll") for (int n = 0; n < 2; ++n) _Pragma("unroll") for (int k = 0; k < 2; ++k) \
;         acc[ai][bj][m][n] = __builtin_amdgcn_mfma_f32_16x16x32_bf16(Bt[n][k], At[m][k], acc[ai][bj][m][n], 0, 0, 0); __builtin_amdgcn_s_setprio(0); } while (0)
; #define PG8_WAIT_V(n) asm volatile("s_waitcnt vmcnt(" #n ")" ::: "memory")
; #define PG8_WAIT_L(n) asm volatile("s_waitcnt lgkmcnt(" #n ")" ::: "memory")
; #define PG8_BAR __builtin_amdgcn_s_barrier()
; #define PG8_SCHED __builtin_amdgcn_sched_barrier(0)
; template <class Epi>
; __device__ __forceinline__ void gemm_phase(LAS unsigned char* lds, const Gemm g, const StaticOrder& S, const Epi& E, const bool perm) {
;     ...
;             PG8_LDA(At, 1, 1); PG8_STAGE(PG8_SA(1, 0), a3, voffA);
;             PG8_BAR; PG8_WAIT_L(0); PG8_MMA(1, 0, At, B0); PG8_BAR; PG8_SCHED;
;             PG8_STAGE(PG8_SB(1, 1), b3 + hstep, voffB);
;             PG8_WAIT_V(6); PG8_BAR; PG8_MMA(1, 1, At, B1); PG8_BAR;
;         }
	ds_read_b128 v[144:147], v248 offset:49152
	ds_read_b128 v[148:151], v248 offset:50176
	ds_read_b128 v[152:155], v248 offset:51200
	ds_read_b128 v[156:159], v248 offset:52224
	ds_read_b128 v[160:163], v248 offset:53248
	ds_read_b128 v[164:167], v248 offset:54272
	ds_read_b128 v[168:171], v248 offset:55296
	ds_read_b128 v[172:175], v248 offset:56320
	v_lshl_add_u64 v[230:231], v[230:231], 0, s[74:75]
	s_mov_b32 m0, s23
	s_nop 0
	global_load_lds_dwordx4 v[230:231], off
	v_lshl_add_u64 v[230:231], v[232:233], 0, s[74:75]
	s_add_i32 m0, s23, 0x2000
	s_nop 0
	global_load_lds_dwordx4 v[230:231], off
	v_lshl_add_u64 v[230:231], v[250:251], 0, s[74:75]
	s_mov_b32 m0, s14
	s_nop 0
	global_load_lds_dwordx4 v[230:231], off
	v_lshl_add_u64 v[230:231], v[252:253], 0, s[74:75]
	s_mov_b32 m0, s15
	s_nop 0
	global_load_lds_dwordx4 v[230:231], off
	s_add_i32 s22, s22, s31
	v_lshl_add_u64 v[230:231], v[238:239], 0, s[74:75]
	s_mov_b32 m0, s22
	s_nop 0
	global_load_lds_dwordx4 v[230:231], off
	v_lshl_add_u64 v[230:231], v[240:241], 0, s[74:75]
	s_add_i32 m0, s22, 0x2000
	s_nop 0
	global_load_lds_dwordx4 v[230:231], off
	s_waitcnt vmcnt(8)
	s_waitcnt lgkmcnt(0)
	s_barrier
	s_setprio 1
	v_mfma_f32_16x16x32_bf16 v[60:63], v[128:131], v[144:147], v[60:63]
	v_mfma_f32_16x16x32_bf16 v[56:59], v[136:139], v[144:147], v[56:59]
	v_mfma_f32_16x16x32_bf16 v[44:47], v[128:131], v[152:155], v[44:47]
	v_mfma_f32_16x16x32_bf16 v[40:43], v[136:139], v[152:155], v[40:43]
	v_mfma_f32_16x16x32_bf16 v[28:31], v[128:131], v[160:163], v[28:31]
	v_mfma_f32_16x16x32_bf16 v[24:27], v[136:139], v[160:163], v[24:27]
	v_mfma_f32_16x16x32_bf16 v[12:15], v[128:131], v[168:171], v[12:15]
	v_mfma_f32_16x16x32_bf16 v[8:11], v[136:139], v[168:171], v[8:11]
	v_mfma_f32_16x16x32_bf16 v[60:63], v[132:135], v[148:151], v[60:63]
	v_mfma_f32_16x16x32_bf16 v[56:59], v[140:143], v[148:151], v[56:59]
	v_mfma_f32_16x16x32_bf16 v[44:47], v[132:135], v[156:159], v[44:47]
	v_mfma_f32_16x16x32_bf16 v[40:43], v[140:143], v[156:159], v[40:43]
	v_mfma_f32_16x16x32_bf16 v[28:31], v[132:135], v[164:167], v[28:31]
	v_mfma_f32_16x16x32_bf16 v[24:27], v[140:143], v[164:167], v[24:27]
	v_mfma_f32_16x16x32_bf16 v[12:15], v[132:135], v[172:175], v[12:15]
	v_mfma_f32_16x16x32_bf16 v[8:11], v[140:143], v[172:175], v[8:11]
	v_mfma_f32_16x16x32_bf16 v[52:55], v[176:179], v[144:147], v[52:55]
	v_mfma_f32_16x16x32_bf16 v[48:51], v[222:225], v[144:147], v[48:51]
	v_mfma_f32_16x16x32_bf16 v[36:39], v[176:179], v[152:155], v[36:39]
	v_mfma_f32_16x16x32_bf16 v[32:35], v[222:225], v[152:155], v[32:35]
	v_mfma_f32_16x16x32_bf16 v[20:23], v[176:179], v[160:163], v[20:23]
	v_mfma_f32_16x16x32_bf16 v[16:19], v[222:225], v[160:163], v[16:19]
	v_mfma_f32_16x16x32_bf16 v[4:7], v[176:179], v[168:171], v[4:7]
	v_mfma_f32_16x16x32_bf16 v[0:3], v[222:225], v[168:171], v[0:3]
	v_mfma_f32_16x16x32_bf16 v[52:55], v[180:183], v[148:151], v[52:55]
	v_mfma_f32_16x16x32_bf16 v[48:51], v[226:229], v[148:151], v[48:51]
	v_mfma_f32_16x16x32_bf16 v[36:39], v[180:183], v[156:159], v[36:39]
	v_mfma_f32_16x16x32_bf16 v[32:35], v[226:229], v[156:159], v[32:35]
	v_mfma_f32_16x16x32_bf16 v[20:23], v[180:183], v[164:167], v[20:23]
	v_mfma_f32_16x16x32_bf16 v[16:19], v[226:229], v[164:167], v[16:19]
	v_mfma_f32_16x16x32_bf16 v[4:7], v[180:183], v[172:175], v[4:7]
	v_mfma_f32_16x16x32_bf16 v[0:3], v[226:229], v[172:175], v[0:3]
	s_setprio 0
	s_addk_i32 s79, 0x80
	s_add_u32 s6, s6, 0x100
	s_addc_u32 s7, s7, 0
	s_add_u32 s55, s55, 0x100
	s_addc_u32 s78, s78, 0
	s_cmp_ge_u32 s61, s65
	s_mov_b32 s60, s61
	s_barrier
	s_cbranch_scc1 .LBB0_470
